# v3 + removed compiler vmcnt(0) at in-proj loop head + attention unit setup issues Q loads before 2nd K/V block (wait vmcnt(8))
# speedup vs baseline: 1.0168x; 1.0084x over previous
; #define PG8_STAGE(bufoff, gbase, voff) do { _Pragma("unroll") for (int _i = 0; _i < 2; ++_i) \
;         __builtin_amdgcn_global_load_lds((const unsigned*)((const char*)(gbase) + (voff)[_i]), (LAS unsigned*)(lds + (bufoff) + ldsw + _i * 8192), 16, 0, 0); } while (0)
; #define PG8_LDA(dst, b, h) do { _Pragma("unroll") for (int m = 0; m < 4; ++m) _Pragma("unroll") for (int k = 0; k < 2; ++k) dst[m][k] = *(const LAS bf16x8*)(lds + PG8_SA(b, h) + aoff + m * 2048 + k * 1024); } while (0)
; #define PG8_LDB(dst, b, h) do { _Pragma("unroll") for (int n = 0; n < 2; ++n) _Pragma("unroll") for (int k = 0; k < 2; ++k) dst[n][k] = *(const LAS bf16x8*)(lds + PG8_SB(b, h) + boff + n * 2048 + k * 1024); } while (0)
; #define PG8_MMA(ai, bj, At, Bt) do { __builtin_amdgcn_s_setprio(1); _Pragma("unroll") for (int m = 0; m < 4; ++m) _Pragma("unroll") for (int n = 0; n < 2; ++n) _Pragma("unroll") for (int k = 0; k < 2; ++k) \
;         acc[ai][bj][m][n] = __builtin_amdgcn_mfma_f32_16x16x32_bf16(Bt[n][k], At[m][k], acc[ai][bj][m][n], 0, 0, 0); __builtin_amdgcn_s_setprio(0); } while (0)
; #define PG8_WAIT_V(n) asm volatile("s_waitcnt vmcnt(" #n ")" ::: "memory")
; #define PG8_WAIT_L(n) asm volatile("s_waitcnt lgkmcnt(" #n ")" ::: "memory")
; #define PG8_BAR __builtin_amdgcn_s_barrier()
; #define PG8_SCHED __builtin_amdgcn_sched_barrier(0)
; template <class Epi, class Sched, bool ALIGN_EPI>
; DI void gemm_phase(LAS unsigned char* lds, const Gemm g, const Sched& S, const Epi& E) {
;     ...
;         for (int t = 0; t < nt; t += 2) {
;             const bool last = (t == nt - 2);
;             const char* a1 = cA + (size_t)(t + 1) * kstep;
;             const char* a2 = last ? nA : cA + (size_t)(t + 2) * kstep; const char* b2 = last ? nB : cB + (size_t)(t + 2) * kstep;
;             const char* a3 = a2 + kstep; const char* b3 = b2 + kstep;
;             PG8_LDB(B0, 0, 0); PG8_LDB(B1, 0, 1); PG8_SCHED; PG8_LDA(At, 0, 0); PG8_STAGE(PG8_SA(1, 1), a1 + hstep, voffA);
;             PG8_WAIT_V(8); PG8_WAIT_L(0); PG8_BAR; PG8_MMA(0, 0, At, B0); PG8_MMA(0, 1, At, B1); PG8_BAR; PG8_SCHED;
;             PG8_LDA(At, 0, 1); PG8_STAGE(PG8_SB(0, 0), b2, voffA); PG8_STAGE(PG8_SB(0, 1), b2 + hstep, voffA); PG8_STAGE(PG8_SA(0, 0), a2, voffA);
;             PG8_WAIT_V(8); PG8_WAIT_L(0); PG8_BAR; PG8_MMA(1, 0, At, B0); PG8_MMA(1, 1, At, B1); PG8_BAR; PG8_SCHED;
.LBB0_104:
	ds_read_b128 v[48:51], v196
	ds_read_b128 v[52:55], v196 offset:1024
	ds_read_b128 v[56:59], v196 offset:2048
	ds_read_b128 v[60:63], v196 offset:3072
	ds_read_b128 v[182:185], v197
	ds_read_b128 v[186:189], v197 offset:1024
	ds_read_b128 v[200:203], v197 offset:2048
	ds_read_b128 v[204:207], v197 offset:3072
	s_add_u32 s8, s0, 0xfffc0080
	s_addc_u32 s9, s1, -1
	s_cmp_eq_u32 s47, 12
	s_cselect_b32 s45, s7, s9
	s_cselect_b32 s44, s11, s8
	s_cselect_b32 s9, s18, s46
	s_cselect_b32 s8, s29, s31
	v_lshl_add_u64 v[224:225], s[0:1], 0, v[174:175]
	s_add_i32 m0, s64, 0xc000
	ds_read_b128 v[208:211], v194
	ds_read_b128 v[212:215], v194 offset:1024
	ds_read_b128 v[216:219], v194 offset:2048
	ds_read_b128 v[220:223], v194 offset:3072
	ds_read_b128 v[228:231], v194 offset:4096
	ds_read_b128 v[232:235], v194 offset:5120
	ds_read_b128 v[236:239], v194 offset:6144
	ds_read_b128 v[240:243], v194 offset:7168
	global_load_lds_dwordx4 v[224:225], off
	v_lshl_add_u64 v[224:225], s[0:1], 0, v[176:177]
	s_add_i32 m0, s64, 0xe000
	s_nop 0
	global_load_lds_dwordx4 v[224:225], off
	s_waitcnt vmcnt(8)
	s_waitcnt lgkmcnt(0)
	s_barrier
	s_setprio 1
	s_waitcnt lgkmcnt(0)
	v_mfma_f32_16x16x32_bf16 v[140:143], v[48:51], v[208:211], v[140:143]
	v_mfma_f32_16x16x32_bf16 v[136:139], v[56:59], v[208:211], v[136:139]
	v_mfma_f32_16x16x32_bf16 v[124:127], v[48:51], v[216:219], v[124:127]
	v_mfma_f32_16x16x32_bf16 v[120:123], v[56:59], v[216:219], v[120:123]
	v_mfma_f32_16x16x32_bf16 v[108:111], v[48:51], v[228:231], v[108:111]
	v_mfma_f32_16x16x32_bf16 v[104:107], v[56:59], v[228:231], v[104:107]
	v_mfma_f32_16x16x32_bf16 v[92:95], v[48:51], v[236:239], v[92:95]
	v_mfma_f32_16x16x32_bf16 v[88:91], v[56:59], v[236:239], v[88:91]
	v_mfma_f32_16x16x32_bf16 v[140:143], v[52:55], v[212:215], v[140:143]
	v_mfma_f32_16x16x32_bf16 v[136:139], v[60:63], v[212:215], v[136:139]
	v_mfma_f32_16x16x32_bf16 v[124:127], v[52:55], v[220:223], v[124:127]
	v_mfma_f32_16x16x32_bf16 v[120:123], v[60:63], v[220:223], v[120:123]
	v_mfma_f32_16x16x32_bf16 v[108:111], v[52:55], v[232:235], v[108:111]
	v_mfma_f32_16x16x32_bf16 v[104:107], v[60:63], v[232:235], v[104:107]
	v_mfma_f32_16x16x32_bf16 v[92:95], v[52:55], v[240:243], v[92:95]
	v_mfma_f32_16x16x32_bf16 v[88:91], v[60:63], v[240:243], v[88:91]
	s_setprio 0
	s_setprio 1
	v_mfma_f32_16x16x32_bf16 v[132:135], v[182:185], v[208:211], v[132:135]
	v_mfma_f32_16x16x32_bf16 v[128:131], v[200:203], v[208:211], v[128:131]
	v_mfma_f32_16x16x32_bf16 v[116:119], v[182:185], v[216:219], v[116:119]
	v_mfma_f32_16x16x32_bf16 v[112:115], v[200:203], v[216:219], v[112:115]
	v_mfma_f32_16x16x32_bf16 v[100:103], v[182:185], v[228:231], v[100:103]
	v_mfma_f32_16x16x32_bf16 v[96:99], v[200:203], v[228:231], v[96:99]
	v_mfma_f32_16x16x32_bf16 v[84:87], v[182:185], v[236:239], v[84:87]
	v_mfma_f32_16x16x32_bf16 v[80:83], v[200:203], v[236:239], v[80:83]
	v_mfma_f32_16x16x32_bf16 v[132:135], v[186:189], v[212:215], v[132:135]
	v_mfma_f32_16x16x32_bf16 v[128:131], v[204:207], v[212:215], v[128:131]
	v_mfma_f32_16x16x32_bf16 v[116:119], v[186:189], v[220:223], v[116:119]
	v_mfma_f32_16x16x32_bf16 v[112:115], v[204:207], v[220:223], v[112:115]
	v_mfma_f32_16x16x32_bf16 v[100:103], v[186:189], v[232:235], v[100:103]
	v_mfma_f32_16x16x32_bf16 v[96:99], v[204:207], v[232:235], v[96:99]
	v_mfma_f32_16x16x32_bf16 v[84:87], v[186:189], v[240:243], v[84:87]
	v_mfma_f32_16x16x32_bf16 v[80:83], v[204:207], v[240:243], v[80:83]
	s_setprio 0
	s_barrier
	s_add_i32 s48, s75, s63
	v_lshl_add_u64 v[224:225], s[8:9], 0, v[146:147]
	s_mov_b32 m0, s48
	ds_read_b128 v[208:211], v194 offset:16384
	ds_read_b128 v[212:215], v194 offset:17408
	ds_read_b128 v[216:219], v194 offset:18432
	ds_read_b128 v[220:223], v194 offset:19456
	ds_read_b128 v[228:231], v194 offset:20480
	ds_read_b128 v[232:235], v194 offset:21504
	ds_read_b128 v[236:239], v194 offset:22528
	ds_read_b128 v[240:243], v194 offset:23552
	global_load_lds_dwordx4 v[224:225], off
	s_add_i32 m0, s48, 0x2000
	s_add_u32 s48, s8, 0x40000
	v_lshl_add_u64 v[244:245], s[8:9], 0, v[148:149]
	s_addc_u32 s49, s9, 0
	s_add_i32 s50, s76, s63
	global_load_lds_dwordx4 v[244:245], off
	v_lshl_add_u64 v[246:247], s[48:49], 0, v[146:147]
	s_mov_b32 m0, s50
	v_lshl_add_u64 v[248:249], s[44:45], 0, v[148:149]
	global_load_lds_dwordx4 v[246:247], off
	v_lshl_add_u64 v[246:247], s[48:49], 0, v[148:149]
	s_add_i32 m0, s50, 0x2000
	s_nop 0
	global_load_lds_dwordx4 v[246:247], off
	v_lshl_add_u64 v[246:247], s[44:45], 0, v[146:147]
	s_mov_b32 m0, s64
	s_nop 0
	global_load_lds_dwordx4 v[246:247], off
	s_mov_b32 m0, s65
	s_nop 0
	global_load_lds_dwordx4 v[248:249], off
	s_waitcnt vmcnt(8)
	s_waitcnt lgkmcnt(0)
	s_barrier
; #define PG8_STAGE(bufoff, gbase, voff) do { _Pragma("unroll") for (int _i = 0; _i < 2; ++_i) \
;         __builtin_amdgcn_global_load_lds((const unsigned*)((const char*)(gbase) + (voff)[_i]), (LAS unsigned*)(lds + (bufoff) + ldsw + _i * 8192), 16, 0, 0); } while (0)
; #define PG8_LDA(dst, b, h) do { _Pragma("unroll") for (int m = 0; m < 4; ++m) _Pragma("unroll") for (int k = 0; k < 2; ++k) dst[m][k] = *(const LAS bf16x8*)(lds + PG8_SA(b, h) + aoff + m * 2048 + k * 1024); } while (0)
; #define PG8_LDB(dst, b, h) do { _Pragma("unroll") for (int n = 0; n < 2; ++n) _Pragma("unroll") for (int k = 0; k < 2; ++k) dst[n][k] = *(const LAS bf16x8*)(lds + PG8_SB(b, h) + boff + n * 2048 + k * 1024); } while (0)
; #define PG8_MMA(ai, bj, At, Bt) do { __builtin_amdgcn_s_setprio(1); _Pragma("unroll") for (int m = 0; m < 4; ++m) _Pragma("unroll") for (int n = 0; n < 2; ++n) _Pragma("unroll") for (int k = 0; k < 2; ++k) \
;         acc[ai][bj][m][n] = __builtin_amdgcn_mfma_f32_16x16x32_bf16(Bt[n][k], At[m][k], acc[ai][bj][m][n], 0, 0, 0); __builtin_amdgcn_s_setprio(0); } while (0)
; #define PG8_WAIT_V(n) asm volatile("s_waitcnt vmcnt(" #n ")" ::: "memory")
; #define PG8_WAIT_L(n) asm volatile("s_waitcnt lgkmcnt(" #n ")" ::: "memory")
; #define PG8_BAR __builtin_amdgcn_s_barrier()
; #define PG8_SCHED __builtin_amdgcn_sched_barrier(0)
; template <class Epi, class Sched, bool ALIGN_EPI>
; DI void gemm_phase(LAS unsigned char* lds, const Gemm g, const Sched& S, const Epi& E) {
;     ...
;             PG8_WAIT_V(8); PG8_WAIT_L(0); PG8_BAR; PG8_MMA(1, 0, At, B0); PG8_MMA(1, 1, At, B1); PG8_BAR; PG8_SCHED;
;             PG8_LDB(B0, 1, 0); PG8_LDB(B1, 1, 1); PG8_SCHED; PG8_LDA(At, 1, 0); PG8_STAGE(PG8_SA(0, 1), a2 + hstep, voffA);
;             PG8_WAIT_V(8); PG8_WAIT_L(0); PG8_BAR; PG8_MMA(0, 0, At, B0); PG8_MMA(0, 1, At, B1); PG8_BAR; PG8_SCHED;
	s_setprio 1
	s_waitcnt lgkmcnt(0)
	v_mfma_f32_16x16x32_bf16 v[76:79], v[48:51], v[208:211], v[76:79]
	v_mfma_f32_16x16x32_bf16 v[72:75], v[56:59], v[208:211], v[72:75]
	v_mfma_f32_16x16x32_bf16 v[44:47], v[48:51], v[216:219], v[44:47]
	v_mfma_f32_16x16x32_bf16 v[40:43], v[56:59], v[216:219], v[40:43]
	v_mfma_f32_16x16x32_bf16 v[28:31], v[48:51], v[228:231], v[28:31]
	v_mfma_f32_16x16x32_bf16 v[24:27], v[56:59], v[228:231], v[24:27]
	v_mfma_f32_16x16x32_bf16 v[12:15], v[48:51], v[236:239], v[12:15]
	v_mfma_f32_16x16x32_bf16 v[8:11], v[56:59], v[236:239], v[8:11]
	v_mfma_f32_16x16x32_bf16 v[76:79], v[52:55], v[212:215], v[76:79]
	v_mfma_f32_16x16x32_bf16 v[72:75], v[60:63], v[212:215], v[72:75]
	v_mfma_f32_16x16x32_bf16 v[44:47], v[52:55], v[220:223], v[44:47]
	v_mfma_f32_16x16x32_bf16 v[40:43], v[60:63], v[220:223], v[40:43]
	v_mfma_f32_16x16x32_bf16 v[28:31], v[52:55], v[232:235], v[28:31]
	v_mfma_f32_16x16x32_bf16 v[24:27], v[60:63], v[232:235], v[24:27]
	v_mfma_f32_16x16x32_bf16 v[12:15], v[52:55], v[240:243], v[12:15]
	v_mfma_f32_16x16x32_bf16 v[8:11], v[60:63], v[240:243], v[8:11]
	s_setprio 0
	s_setprio 1
	v_mfma_f32_16x16x32_bf16 v[36:39], v[182:185], v[216:219], v[36:39]
	v_mfma_f32_16x16x32_bf16 v[32:35], v[200:203], v[216:219], v[32:35]
	v_mfma_f32_16x16x32_bf16 v[20:23], v[182:185], v[228:231], v[20:23]
	v_mfma_f32_16x16x32_bf16 v[16:19], v[200:203], v[228:231], v[16:19]
	v_mfma_f32_16x16x32_bf16 v[4:7], v[182:185], v[236:239], v[4:7]
	v_mfma_f32_16x16x32_bf16 v[0:3], v[200:203], v[236:239], v[0:3]
	v_mfma_f32_16x16x32_bf16 v[48:51], v[182:185], v[208:211], v[68:71]
	v_mfma_f32_16x16x32_bf16 v[52:55], v[200:203], v[208:211], v[64:67]
	v_mfma_f32_16x16x32_bf16 v[36:39], v[186:189], v[220:223], v[36:39]
	v_mfma_f32_16x16x32_bf16 v[32:35], v[204:207], v[220:223], v[32:35]
	v_mfma_f32_16x16x32_bf16 v[20:23], v[186:189], v[232:235], v[20:23]
	v_mfma_f32_16x16x32_bf16 v[16:19], v[204:207], v[232:235], v[16:19]
	v_mfma_f32_16x16x32_bf16 v[4:7], v[186:189], v[240:243], v[4:7]
	v_mfma_f32_16x16x32_bf16 v[0:3], v[204:207], v[240:243], v[0:3]
	v_mfma_f32_16x16x32_bf16 v[48:51], v[186:189], v[212:215], v[48:51]
	v_mfma_f32_16x16x32_bf16 v[52:55], v[204:207], v[212:215], v[52:55]
	s_setprio 0
	s_barrier
	s_add_i32 s48, 0, 0x18000
	s_add_i32 s49, 0, 0x1c000
	v_add_u32_e32 v68, s48, v157
	v_add_u32_e32 v150, s49, v157
	ds_read_b128 v[56:59], v68
	ds_read_b128 v[60:63], v68 offset:1024
	ds_read_b128 v[64:67], v68 offset:2048
	ds_read_b128 v[68:71], v68 offset:3072
	ds_read_b128 v[182:185], v150
	ds_read_b128 v[186:189], v150 offset:1024
	ds_read_b128 v[200:203], v150 offset:2048
	ds_read_b128 v[204:207], v150 offset:3072
	s_add_u32 s44, s44, 0x40000
	s_addc_u32 s45, s45, 0
	s_mov_b32 m0, s66
	v_lshl_add_u64 v[250:251], s[44:45], 0, v[146:147]
	ds_read_b128 v[208:211], v194 offset:32768
	ds_read_b128 v[212:215], v194 offset:33792
	ds_read_b128 v[216:219], v194 offset:34816
	ds_read_b128 v[220:223], v194 offset:35840
	ds_read_b128 v[228:231], v194 offset:36864
	ds_read_b128 v[232:235], v194 offset:37888
	ds_read_b128 v[236:239], v194 offset:38912
	ds_read_b128 v[240:243], v194 offset:39936
	global_load_lds_dwordx4 v[250:251], off
	v_lshl_add_u64 v[250:251], s[44:45], 0, v[148:149]
	s_mov_b32 m0, s67
	s_nop 0
	global_load_lds_dwordx4 v[250:251], off
	s_waitcnt vmcnt(8)
	s_waitcnt lgkmcnt(0)
	s_barrier
	s_setprio 1
	s_waitcnt lgkmcnt(0)
	v_mfma_f32_16x16x32_bf16 v[140:143], v[56:59], v[208:211], v[140:143]
	v_mfma_f32_16x16x32_bf16 v[136:139], v[64:67], v[208:211], v[136:139]
	v_mfma_f32_16x16x32_bf16 v[124:127], v[56:59], v[216:219], v[124:127]
	v_mfma_f32_16x16x32_bf16 v[120:123], v[64:67], v[216:219], v[120:123]
	v_mfma_f32_16x16x32_bf16 v[108:111], v[56:59], v[228:231], v[108:111]
	v_mfma_f32_16x16x32_bf16 v[104:107], v[64:67], v[228:231], v[104:107]
	v_mfma_f32_16x16x32_bf16 v[92:95], v[56:59], v[236:239], v[92:95]
	v_mfma_f32_16x16x32_bf16 v[88:91], v[64:67], v[236:239], v[88:91]
	v_mfma_f32_16x16x32_bf16 v[140:143], v[60:63], v[212:215], v[140:143]
	v_mfma_f32_16x16x32_bf16 v[136:139], v[68:71], v[212:215], v[136:139]
	v_mfma_f32_16x16x32_bf16 v[124:127], v[60:63], v[220:223], v[124:127]
	v_mfma_f32_16x16x32_bf16 v[120:123], v[68:71], v[220:223], v[120:123]
	v_mfma_f32_16x16x32_bf16 v[108:111], v[60:63], v[232:235], v[108:111]
	v_mfma_f32_16x16x32_bf16 v[104:107], v[68:71], v[232:235], v[104:107]
	v_mfma_f32_16x16x32_bf16 v[92:95], v[60:63], v[240:243], v[92:95]
	v_mfma_f32_16x16x32_bf16 v[88:91], v[68:71], v[240:243], v[88:91]
	s_setprio 0
	s_setprio 1
	v_mfma_f32_16x16x32_bf16 v[132:135], v[182:185], v[208:211], v[132:135]
	v_mfma_f32_16x16x32_bf16 v[128:131], v[200:203], v[208:211], v[128:131]
	v_mfma_f32_16x16x32_bf16 v[116:119], v[182:185], v[216:219], v[116:119]
	v_mfma_f32_16x16x32_bf16 v[112:115], v[200:203], v[216:219], v[112:115]
	v_mfma_f32_16x16x32_bf16 v[100:103], v[182:185], v[228:231], v[100:103]
	v_mfma_f32_16x16x32_bf16 v[96:99], v[200:203], v[228:231], v[96:99]
	v_mfma_f32_16x16x32_bf16 v[84:87], v[182:185], v[236:239], v[84:87]
	v_mfma_f32_16x16x32_bf16 v[80:83], v[200:203], v[236:239], v[80:83]
	v_mfma_f32_16x16x32_bf16 v[132:135], v[186:189], v[212:215], v[132:135]
	v_mfma_f32_16x16x32_bf16 v[128:131], v[204:207], v[212:215], v[128:131]
	v_mfma_f32_16x16x32_bf16 v[116:119], v[186:189], v[220:223], v[116:119]
	v_mfma_f32_16x16x32_bf16 v[112:115], v[204:207], v[220:223], v[112:115]
	v_mfma_f32_16x16x32_bf16 v[100:103], v[186:189], v[232:235], v[100:103]
	v_mfma_f32_16x16x32_bf16 v[96:99], v[204:207], v[232:235], v[96:99]
	v_mfma_f32_16x16x32_bf16 v[84:87], v[186:189], v[240:243], v[84:87]
	v_mfma_f32_16x16x32_bf16 v[80:83], v[204:207], v[240:243], v[80:83]
	s_setprio 0
	s_barrier
; #define PG8_STAGE(bufoff, gbase, voff) do { _Pragma("unroll") for (int _i = 0; _i < 2; ++_i) \
;         __builtin_amdgcn_global_load_lds((const unsigned*)((const char*)(gbase) + (voff)[_i]), (LAS unsigned*)(lds + (bufoff) + ldsw + _i * 8192), 16, 0, 0); } while (0)
; #define PG8_LDA(dst, b, h) do { _Pragma("unroll") for (int m = 0; m < 4; ++m) _Pragma("unroll") for (int k = 0; k < 2; ++k) dst[m][k] = *(const LAS bf16x8*)(lds + PG8_SA(b, h) + aoff + m * 2048 + k * 1024); } while (0)
; #define PG8_MMA(ai, bj, At, Bt) do { __builtin_amdgcn_s_setprio(1); _Pragma("unroll") for (int m = 0; m < 4; ++m) _Pragma("unroll") for (int n = 0; n < 2; ++n) _Pragma("unroll") for (int k = 0; k < 2; ++k) \
;         acc[ai][bj][m][n] = __builtin_amdgcn_mfma_f32_16x16x32_bf16(Bt[n][k], At[m][k], acc[ai][bj][m][n], 0, 0, 0); __builtin_amdgcn_s_setprio(0); } while (0)
; #define PG8_WAIT_V(n) asm volatile("s_waitcnt vmcnt(" #n ")" ::: "memory")
; #define PG8_WAIT_L(n) asm volatile("s_waitcnt lgkmcnt(" #n ")" ::: "memory")
; #define PG8_BAR __builtin_amdgcn_s_barrier()
; #define PG8_SCHED __builtin_amdgcn_sched_barrier(0)
; template <class Epi, class Sched, bool ALIGN_EPI>
; DI void gemm_phase(LAS unsigned char* lds, const Gemm g, const Sched& S, const Epi& E) {
;     ...
;             PG8_LDA(At, 1, 1); PG8_STAGE(PG8_SB(1, 0), b3, voffA); PG8_STAGE(PG8_SB(1, 1), b3 + hstep, voffA); PG8_STAGE(PG8_SA(1, 0), a3, voffA);
;             PG8_WAIT_V(8); PG8_WAIT_L(0); PG8_BAR; PG8_MMA(1, 0, At, B0); PG8_MMA(1, 1, At, B1); PG8_BAR; PG8_SCHED;
;         }
;         if constexpr (ALIGN_EPI) { if (wr == 0) PG8_BAR; }
	s_add_i32 s44, s48, s63
	v_lshl_add_u64 v[224:225], v[224:225], 0, s[22:23]
	s_mov_b32 m0, s44
	ds_read_b128 v[208:211], v194 offset:49152
	ds_read_b128 v[212:215], v194 offset:50176
	ds_read_b128 v[216:219], v194 offset:51200
	ds_read_b128 v[220:223], v194 offset:52224
	ds_read_b128 v[228:231], v194 offset:53248
	ds_read_b128 v[232:235], v194 offset:54272
	ds_read_b128 v[236:239], v194 offset:55296
	ds_read_b128 v[240:243], v194 offset:56320
	global_load_lds_dwordx4 v[224:225], off
	s_add_i32 m0, s44, 0x2000
	s_add_u32 s8, s8, 0x40080
	v_lshl_add_u64 v[224:225], v[244:245], 0, s[22:23]
	s_addc_u32 s9, s9, 0
	s_add_i32 s44, s49, s63
	global_load_lds_dwordx4 v[224:225], off
	v_lshl_add_u64 v[224:225], s[8:9], 0, v[146:147]
	s_mov_b32 m0, s44
	s_nop 0
	global_load_lds_dwordx4 v[224:225], off
	v_lshl_add_u64 v[224:225], s[8:9], 0, v[148:149]
	s_add_i32 m0, s44, 0x2000
	s_nop 0
	global_load_lds_dwordx4 v[224:225], off
	v_lshl_add_u64 v[224:225], v[246:247], 0, s[22:23]
	s_mov_b32 m0, s70
	s_nop 0
	global_load_lds_dwordx4 v[224:225], off
	v_lshl_add_u64 v[224:225], v[248:249], 0, s[22:23]
	s_mov_b32 m0, s71
	s_nop 0
	global_load_lds_dwordx4 v[224:225], off
	s_waitcnt vmcnt(8)
	s_waitcnt lgkmcnt(0)
	s_barrier
	s_setprio 1
	s_waitcnt lgkmcnt(0)
	v_mfma_f32_16x16x32_bf16 v[76:79], v[56:59], v[208:211], v[76:79]
	v_mfma_f32_16x16x32_bf16 v[72:75], v[64:67], v[208:211], v[72:75]
	v_mfma_f32_16x16x32_bf16 v[44:47], v[56:59], v[216:219], v[44:47]
	v_mfma_f32_16x16x32_bf16 v[40:43], v[64:67], v[216:219], v[40:43]
	v_mfma_f32_16x16x32_bf16 v[28:31], v[56:59], v[228:231], v[28:31]
	v_mfma_f32_16x16x32_bf16 v[24:27], v[64:67], v[228:231], v[24:27]
	v_mfma_f32_16x16x32_bf16 v[12:15], v[56:59], v[236:239], v[12:15]
	v_mfma_f32_16x16x32_bf16 v[8:11], v[64:67], v[236:239], v[8:11]
	v_mfma_f32_16x16x32_bf16 v[76:79], v[60:63], v[212:215], v[76:79]
	v_mfma_f32_16x16x32_bf16 v[72:75], v[68:71], v[212:215], v[72:75]
	v_mfma_f32_16x16x32_bf16 v[44:47], v[60:63], v[220:223], v[44:47]
	v_mfma_f32_16x16x32_bf16 v[40:43], v[68:71], v[220:223], v[40:43]
	v_mfma_f32_16x16x32_bf16 v[28:31], v[60:63], v[232:235], v[28:31]
	v_mfma_f32_16x16x32_bf16 v[24:27], v[68:71], v[232:235], v[24:27]
	v_mfma_f32_16x16x32_bf16 v[12:15], v[60:63], v[240:243], v[12:15]
	v_mfma_f32_16x16x32_bf16 v[8:11], v[68:71], v[240:243], v[8:11]
	s_setprio 0
	s_setprio 1
	v_mfma_f32_16x16x32_bf16 v[48:51], v[182:185], v[208:211], v[48:51]
	v_mfma_f32_16x16x32_bf16 v[68:71], v[186:189], v[212:215], v[48:51]
	v_mfma_f32_16x16x32_bf16 v[48:51], v[200:203], v[208:211], v[52:55]
	v_mfma_f32_16x16x32_bf16 v[36:39], v[182:185], v[216:219], v[36:39]
	v_mfma_f32_16x16x32_bf16 v[32:35], v[200:203], v[216:219], v[32:35]
	v_mfma_f32_16x16x32_bf16 v[20:23], v[182:185], v[228:231], v[20:23]
	v_mfma_f32_16x16x32_bf16 v[16:19], v[200:203], v[228:231], v[16:19]
	v_mfma_f32_16x16x32_bf16 v[4:7], v[182:185], v[236:239], v[4:7]
	v_mfma_f32_16x16x32_bf16 v[0:3], v[200:203], v[236:239], v[0:3]
	v_mfma_f32_16x16x32_bf16 v[64:67], v[204:207], v[212:215], v[48:51]
	v_mfma_f32_16x16x32_bf16 v[36:39], v[186:189], v[220:223], v[36:39]
	v_mfma_f32_16x16x32_bf16 v[32:35], v[204:207], v[220:223], v[32:35]
	v_mfma_f32_16x16x32_bf16 v[20:23], v[186:189], v[232:235], v[20:23]
	v_mfma_f32_16x16x32_bf16 v[16:19], v[204:207], v[232:235], v[16:19]
	v_mfma_f32_16x16x32_bf16 v[4:7], v[186:189], v[240:243], v[4:7]
	v_mfma_f32_16x16x32_bf16 v[0:3], v[204:207], v[240:243], v[0:3]
	s_setprio 0
	s_barrier
	s_add_i32 s47, s47, 2
	s_add_u32 s0, s0, 0x100
	s_addc_u32 s1, s1, 0
	s_add_u32 s31, s31, 0x100
	s_addc_u32 s46, s46, 0
	s_cmp_gt_u32 s47, 13
	s_cbranch_scc0 .LBB0_104
	s_and_b64 vcc, exec, s[24:25]
	s_cbranch_vccz .LBB0_107
	s_barrier

; #define LAS __attribute__((address_space(3)))
; template <bool ISB>
; DI void attn_unit(int u, int hq, int qoff, int nq, const bf16_t* Qb, const bf16_t* Kb, const bf16_t* Vtb, bf16_t* O, const float* sinks, const LAS float* biasL, LAS unsigned char* ring, int lane) {
;     ...
;     asm volatile("s_waitcnt vmcnt(0) lgkmcnt(0)" ::: "memory");
;     kv_dma(Kp, Vp, blk0, ring);
;     kv_dma(Kp, Vp, blk0 + 1, ring + 8192);
;     bf16x8 qf[2][4];
; #pragma unroll
;     for (int qb = 0; qb < 2; ++qb)
; #pragma unroll
;         for (int ds = 0; ds < 4; ++ds) qf[qb][ds] = *(const bf16x8*)(Qp + (qb < nq ? 32 * qb + r : r) * 64 + 16 * ds + 8 * hh);
;     f32x16 o[2][2];
; #pragma unroll
;     for (int a = 0; a < 2; ++a)
; #pragma unroll
;         for (int b = 0; b < 2; ++b)
; #pragma unroll
;             for (int i = 0; i < 16; ++i) o[a][b][i] = 0.f;
;     float mrun[2], lrun[2];
; #pragma unroll
;     for (int a = 0; a < 2; ++a) {
;         if (ISB) { mrun[a] = sinks[hq] * LOG2E; lrun[a] = hh ? 0.f : 1.f; }
;         else { mrun[a] = -1e30f; lrun[a] = 0.f; } }
;     const LAS float* biasR = biasL + hq * 256;
;     const float bconst = ISB ? 0.f : biasR[0];
;     asm volatile("s_waitcnt vmcnt(0)" ::: "memory");
.LBB0_615:
	s_ashr_i32 s1, s6, 31
	s_add_u32 s0, s33, s6
	s_addc_u32 s1, 0, s1
	s_lshl_b64 s[26:27], s[0:1], 7
	s_ashr_i32 s0, s4, 5
	s_add_i32 s0, s0, s7
	s_mov_b32 s28, s0
	s_mov_b32 s92, s7
	s_ashr_i32 s1, s0, 31
	s_lshl_b64 s[4:5], s[0:1], 12
	s_mov_b32 m0, s31
	s_waitcnt lgkmcnt(0)
	v_lshl_add_u64 v[0:1], v[162:163], 0, s[4:5]
	global_load_lds_dwordx4 v[0:1], off
	v_lshl_add_u64 v[2:3], v[0:1], 0, s[16:17]
	s_mov_b32 m0, s43
	s_nop 0
	global_load_lds_dwordx4 v[2:3], off
	v_lshl_add_u64 v[2:3], v[0:1], 0, s[18:19]
	s_mov_b32 m0, s44
	v_lshl_add_u64 v[0:1], v[0:1], 0, s[20:21]
	global_load_lds_dwordx4 v[2:3], off
	s_mov_b32 m0, s45
	s_nop 0
	global_load_lds_dwordx4 v[0:1], off
	v_lshl_add_u64 v[0:1], v[164:165], 0, s[4:5]
	s_mov_b32 m0, s46
	v_lshl_add_u64 v[2:3], v[0:1], 0, s[16:17]
	global_load_lds_dwordx4 v[0:1], off
	s_mov_b32 m0, s47
	s_add_u32 s4, s4, 0x1000
	global_load_lds_dwordx4 v[2:3], off
	v_lshl_add_u64 v[2:3], v[0:1], 0, s[18:19]
	s_mov_b32 m0, s48
	v_lshl_add_u64 v[0:1], v[0:1], 0, s[20:21]
	global_load_lds_dwordx4 v[2:3], off
	s_mov_b32 m0, s49
	s_addc_u32 s5, s5, 0
	global_load_lds_dwordx4 v[0:1], off
	v_lshl_add_u64 v[0:1], v[166:167], 0, s[26:27]
	global_load_dwordx4 v[96:99], v[0:1], off
	global_load_dwordx4 v[100:103], v[0:1], off offset:32
	global_load_dwordx4 v[104:107], v[0:1], off offset:64
	global_load_dwordx4 v[108:111], v[0:1], off offset:96
	v_add_co_u32_e32 v0, vcc, 0x1000, v0
	s_nop 1
	v_addc_co_u32_e32 v1, vcc, 0, v1, vcc
	global_load_dwordx4 v[112:115], v[0:1], off
	global_load_dwordx4 v[116:119], v[0:1], off offset:32
	global_load_dwordx4 v[120:123], v[0:1], off offset:64
	global_load_dwordx4 v[124:127], v[0:1], off offset:96
	global_load_dword v66, v161, s[14:15]
	v_lshl_add_u64 v[0:1], v[162:163], 0, s[4:5]
	s_mov_b32 m0, s50
	v_lshl_add_u64 v[2:3], v[0:1], 0, s[16:17]
	global_load_lds_dwordx4 v[0:1], off
	s_mov_b32 m0, s51
	s_cmp_lt_u32 s7, 6
	global_load_lds_dwordx4 v[2:3], off
	v_lshl_add_u64 v[2:3], v[0:1], 0, s[18:19]
	s_mov_b32 m0, s52
	v_lshl_add_u64 v[0:1], v[0:1], 0, s[20:21]
	global_load_lds_dwordx4 v[2:3], off
	s_mov_b32 m0, s53
	s_nop 0
	global_load_lds_dwordx4 v[0:1], off
	v_lshl_add_u64 v[0:1], v[164:165], 0, s[4:5]
	s_mov_b32 m0, s54
	v_lshl_add_u64 v[2:3], v[0:1], 0, s[16:17]
	global_load_lds_dwordx4 v[0:1], off
	s_mov_b32 m0, s55
	s_mov_b64 s[4:5], -1
	global_load_lds_dwordx4 v[2:3], off
	v_lshl_add_u64 v[2:3], v[0:1], 0, s[18:19]
	s_mov_b32 m0, s56
	v_lshl_add_u64 v[0:1], v[0:1], 0, s[20:21]
	global_load_lds_dwordx4 v[2:3], off
	s_mov_b32 m0, s57
	s_nop 0
	global_load_lds_dwordx4 v[0:1], off
	s_waitcnt vmcnt(8)
	s_cbranch_scc1 .LBB0_617
	v_and_b32_e32 v0, 64, v186
	v_xor_b32_e32 v156, 32, v186
	v_add_u32_e32 v157, 64, v0
	s_mov_b64 s[4:5], 0

; #define LAS __attribute__((address_space(3)))
; template <bool ISB>
; DI void attn_unit(int u, int hq, int qoff, int nq, const bf16_t* Qb, const bf16_t* Kb, const bf16_t* Vtb, bf16_t* O, const float* sinks, const LAS float* biasL, LAS unsigned char* ring, int lane) {
;     ...
;     asm volatile("s_waitcnt vmcnt(0) lgkmcnt(0)" ::: "memory");
;     kv_dma(Kp, Vp, blk0, ring);
;     kv_dma(Kp, Vp, blk0 + 1, ring + 8192);
;     bf16x8 qf[2][4];
; #pragma unroll
;     for (int qb = 0; qb < 2; ++qb)
; #pragma unroll
;         for (int ds = 0; ds < 4; ++ds) qf[qb][ds] = *(const bf16x8*)(Qp + (qb < nq ? 32 * qb + r : r) * 64 + 16 * ds + 8 * hh);
;     f32x16 o[2][2];
; #pragma unroll
;     for (int a = 0; a < 2; ++a)
; #pragma unroll
;         for (int b = 0; b < 2; ++b)
; #pragma unroll
;             for (int i = 0; i < 16; ++i) o[a][b][i] = 0.f;
;     float mrun[2], lrun[2];
; #pragma unroll
;     for (int a = 0; a < 2; ++a) {
;         if (ISB) { mrun[a] = sinks[hq] * LOG2E; lrun[a] = hh ? 0.f : 1.f; }
;         else { mrun[a] = -1e30f; lrun[a] = 0.f; } }
;     const LAS float* biasR = biasL + hq * 256;
;     const float bconst = ISB ? 0.f : biasR[0];
;     asm volatile("s_waitcnt vmcnt(0)" ::: "memory");
; __global__ void __launch_bounds__(512, 2) fwd_kernel(Args a_byval) {
;     ...
;             if (k < 10u) { const unsigned i = (unsigned)bx + 256u * (k < 8u ? k : 8u); const int nq = k < 8u ? 2 : 1, qoff = k == 9u ? 32 : 0;
;                 attn_unit<false>(287 - (int)(i >> 3), (int)(i & 7), qoff, nq, (const bf16_t*)(ws + WS_QA), (const bf16_t*)(ws + WS_KA), (const bf16_t*)(ws + WS_VTA), (bf16_t*)(ws + WS_O), nullptr, biasL, lds + wave * 16384, lane); }
.LBB0_647:
	s_cmp_eq_u32 s12, 9
	s_cselect_b32 s93, 32, 0
	s_ashr_i32 s0, s91, 31
	s_add_u32 s5, s33, s91
	s_addc_u32 s1, 0, s0
	s_ashr_i32 s4, s4, 5
	s_add_i32 s28, s4, s92
	s_ashr_i32 s29, s28, 31
	s_or_b32 s0, s5, s93
	s_lshl_b64 s[4:5], s[28:29], 12
	s_mov_b32 m0, s31
	s_waitcnt lgkmcnt(0)
	v_lshl_add_u64 v[0:1], v[168:169], 0, s[4:5]
	global_load_lds_dwordx4 v[0:1], off
	v_lshl_add_u64 v[2:3], v[0:1], 0, s[16:17]
	s_mov_b32 m0, s43
	s_lshl_b64 s[0:1], s[0:1], 7
	global_load_lds_dwordx4 v[2:3], off
	v_lshl_add_u64 v[2:3], v[0:1], 0, s[18:19]
	s_mov_b32 m0, s44
	v_lshl_add_u64 v[0:1], v[0:1], 0, s[20:21]
	global_load_lds_dwordx4 v[2:3], off
	s_mov_b32 m0, s45
	s_add_u32 s6, s4, 0x1000
	global_load_lds_dwordx4 v[0:1], off
	v_lshl_add_u64 v[0:1], v[170:171], 0, s[4:5]
	s_mov_b32 m0, s46
	v_lshl_add_u64 v[2:3], v[0:1], 0, s[16:17]
	global_load_lds_dwordx4 v[0:1], off
	s_mov_b32 m0, s47
	s_addc_u32 s7, s5, 0
	global_load_lds_dwordx4 v[2:3], off
	v_lshl_add_u64 v[2:3], v[0:1], 0, s[18:19]
	s_mov_b32 m0, s48
	v_lshl_add_u64 v[0:1], v[0:1], 0, s[20:21]
	global_load_lds_dwordx4 v[2:3], off
	s_mov_b32 m0, s49
	s_cmp_lt_u32 s12, 8
	global_load_lds_dwordx4 v[0:1], off
	s_cselect_b64 s[26:27], -1, 0
	v_lshl_add_u64 v[0:1], v[172:173], 0, s[0:1]
	s_and_b64 s[0:1], s[26:27], exec
	v_lshl_add_u64 v[2:3], v[0:1], 0, v[160:161]
	s_cselect_b32 s0, 32, 0
	global_load_dwordx4 v[98:101], v[2:3], off
	global_load_dwordx4 v[102:105], v[2:3], off offset:32
	global_load_dwordx4 v[106:109], v[2:3], off offset:64
	global_load_dwordx4 v[110:113], v[2:3], off offset:96
	v_or_b32_e32 v2, s0, v182
	v_lshlrev_b32_e32 v2, 7, v2
	v_mov_b32_e32 v3, v161
	v_lshl_add_u64 v[0:1], v[0:1], 0, v[2:3]
	global_load_dwordx4 v[114:117], v[0:1], off
	global_load_dwordx4 v[118:121], v[0:1], off offset:32
	global_load_dwordx4 v[122:125], v[0:1], off offset:64
	global_load_dwordx4 v[126:129], v[0:1], off offset:96
	v_lshl_add_u64 v[0:1], v[168:169], 0, s[6:7]
	s_mov_b32 m0, s50
	v_lshl_add_u64 v[2:3], v[0:1], 0, s[16:17]
	global_load_lds_dwordx4 v[0:1], off
	s_mov_b32 m0, s51
	s_waitcnt lgkmcnt(0)
	global_load_lds_dwordx4 v[2:3], off
	v_lshl_add_u64 v[2:3], v[0:1], 0, s[18:19]
	s_mov_b32 m0, s52
	v_lshl_add_u64 v[0:1], v[0:1], 0, s[20:21]
	global_load_lds_dwordx4 v[2:3], off
	s_mov_b32 m0, s53
	s_nop 0
	global_load_lds_dwordx4 v[0:1], off
	v_lshl_add_u64 v[0:1], v[170:171], 0, s[6:7]
	s_mov_b32 m0, s54
	v_lshl_add_u64 v[2:3], v[0:1], 0, s[16:17]
	global_load_lds_dwordx4 v[0:1], off
	s_mov_b32 m0, s55
	s_nop 0
	global_load_lds_dwordx4 v[2:3], off
	v_lshl_add_u64 v[2:3], v[0:1], 0, s[18:19]
	s_mov_b32 m0, s56
	v_lshl_add_u64 v[0:1], v[0:1], 0, s[20:21]
	global_load_lds_dwordx4 v[2:3], off
	s_mov_b32 m0, s57
	s_nop 0
	global_load_lds_dwordx4 v[0:1], off
	v_mov_b32_e32 v0, s34
	ds_read_b32 v189, v0
	s_waitcnt vmcnt(8)
	s_cmp_lt_u32 s92, 18
	s_mov_b64 s[0:1], -1
	s_cbranch_scc1 .LBB0_649
	v_mbcnt_hi_u32_b32 v191, -1, v185
	v_and_b32_e32 v0, 64, v191
	v_xor_b32_e32 v192, 32, v191
	v_add_u32_e32 v193, 64, v0
	s_mov_b64 s[0:1], 0
